# gMLP item: the 8 spatial-weight loads issued back to back with counted waits instead of one vmcnt(0) round trip each
# speedup vs baseline: 1.0165x; 1.0032x over previous
.LBB0_264:
	s_or_b64 exec, exec, s[6:7]
	s_and_b32 s2, s24, 7
	s_or_b32 s6, s2, s0
	s_ashr_i32 s7, s6, 31
	v_readlane_b32 s72, v252, 9
	s_lshl_b64 s[8:9], s[6:7], 16
	v_readlane_b32 s82, v252, 19
	v_readlane_b32 s83, v252, 20
	s_add_u32 s8, s82, s8
	v_ashrrev_i32_e32 v1, 31, v0
	s_addc_u32 s9, s83, s9
	s_waitcnt vmcnt(3)
	v_lshl_add_u64 v[136:137], v[0:1], 2, s[8:9]
	v_mov_b32_e32 v138, 0x2000
	v_mov_b32_e32 v139, 0
	global_load_dwordx4 v[104:107], v[136:137], off
	v_lshl_add_u64 v[136:137], v[136:137], 0, v[138:139]
	global_load_dwordx4 v[108:111], v[136:137], off
	v_lshl_add_u64 v[136:137], v[136:137], 0, v[138:139]
	global_load_dwordx4 v[112:115], v[136:137], off
	v_lshl_add_u64 v[136:137], v[136:137], 0, v[138:139]
	global_load_dwordx4 v[116:119], v[136:137], off
	v_lshl_add_u64 v[136:137], v[136:137], 0, v[138:139]
	global_load_dwordx4 v[120:123], v[136:137], off
	v_lshl_add_u64 v[136:137], v[136:137], 0, v[138:139]
	global_load_dwordx4 v[124:127], v[136:137], off
	v_lshl_add_u64 v[136:137], v[136:137], 0, v[138:139]
	global_load_dwordx4 v[128:131], v[136:137], off
	v_lshl_add_u64 v[136:137], v[136:137], 0, v[138:139]
	global_load_dwordx4 v[132:135], v[136:137], off
	s_waitcnt vmcnt(10)
	v_lshlrev_b32_e32 v8, 3, v68
	v_and_b32_e32 v2, 0xf8, v8
	v_add_u32_e32 v2, 0, v2
	v_ashrrev_i32_e32 v3, 7, v0
	s_movk_i32 s3, 0x110
	v_ashrrev_i32_e32 v20, 4, v68
	v_lshlrev_b32_e32 v26, 4, v68
	v_and_b32_e32 v69, 0x78, v8
	s_lshl_b32 s2, s2, 8
	v_mov_b64_e32 v[66:67], s[54:55]
	s_mov_b64 s[60:61], 0x1000
	v_bfe_u32 v24, v8, 5, 2
	v_and_b32_e32 v21, 48, v20
	v_add_u32_e32 v29, 32, v20
	v_and_b32_e32 v25, 63, v68
	v_bfe_u32 v102, v68, 5, 1
	v_readlane_b32 s73, v252, 10
	v_readlane_b32 s74, v252, 11
	v_readlane_b32 s75, v252, 12
	v_readlane_b32 s76, v252, 13
	v_readlane_b32 s77, v252, 14
	v_readlane_b32 s78, v252, 15
	v_readlane_b32 s79, v252, 16
	v_readlane_b32 s80, v252, 17
	v_readlane_b32 s81, v252, 18
	v_readlane_b32 s84, v252, 21
	v_readlane_b32 s85, v252, 22
	v_readlane_b32 s86, v252, 23
	v_readlane_b32 s87, v252, 24
	s_waitcnt vmcnt(7)
	v_cvt_pk_bf16_f32 v4, v104, v105
	v_cvt_pk_bf16_f32 v5, v106, v107
	v_mad_u64_u32 v[6:7], s[26:27], v3, s3, v[2:3]
	ds_write_b64 v6, v[4:5]
	s_waitcnt vmcnt(6)
	v_cvt_pk_bf16_f32 v4, v108, v109
	v_cvt_pk_bf16_f32 v5, v110, v111
	ds_write_b64 v6, v[4:5] offset:4352
	s_waitcnt vmcnt(5)
	v_cvt_pk_bf16_f32 v4, v112, v113
	v_cvt_pk_bf16_f32 v5, v114, v115
	ds_write_b64 v6, v[4:5] offset:8704
	s_waitcnt vmcnt(4)
	v_cvt_pk_bf16_f32 v4, v116, v117
	v_cvt_pk_bf16_f32 v5, v118, v119
	ds_write_b64 v6, v[4:5] offset:13056
	s_waitcnt vmcnt(3)
	v_cvt_pk_bf16_f32 v4, v120, v121
	v_cvt_pk_bf16_f32 v5, v122, v123
	ds_write_b64 v6, v[4:5] offset:17408
	s_waitcnt vmcnt(2)
	v_cvt_pk_bf16_f32 v4, v124, v125
	v_cvt_pk_bf16_f32 v5, v126, v127
	ds_write_b64 v6, v[4:5] offset:21760
	s_waitcnt vmcnt(1)
	v_cvt_pk_bf16_f32 v4, v128, v129
	v_cvt_pk_bf16_f32 v5, v130, v131
	ds_write_b64 v6, v[4:5] offset:26112
	s_waitcnt vmcnt(0)
	v_cvt_pk_bf16_f32 v4, v132, v133
	v_cvt_pk_bf16_f32 v5, v134, v135
	ds_write_b64 v6, v[4:5] offset:30464
	s_add_i32 s3, 0, 0x18800
	v_lshrrev_b32_e32 v0, 1, v20
	v_and_b32_e32 v1, 3, v20
	v_and_or_b32 v0, v0, 4, v1
	v_and_b32_e32 v1, 48, v26
	v_lshl_or_b32 v28, v0, 6, v1
	v_add_u32_e32 v0, s25, v20
	v_or_b32_e32 v2, s2, v69
	v_mad_i64_i32 v[0:1], s[8:9], v0, s69, v[66:67]
	v_lshl_add_u64 v[18:19], v[0:1], 0, s[60:61]
	v_lshlrev_b32_e32 v64, 1, v2
	v_lshl_add_u64 v[0:1], v[18:19], 0, v[64:65]
	s_waitcnt lgkmcnt(0)
	s_barrier
	global_load_dwordx4 v[30:33], v[0:1], off nt
	v_lshlrev_b32_e32 v0, 2, v20
	s_add_i32 s8, 0, 0x18a00
	v_add_u32_e32 v36, s3, v0
	v_add_u32_e32 v37, s8, v0
	v_lshlrev_b32_e32 v27, 2, v2
	ds_read_b32 v16, v36
	ds_read_b32 v22, v37
	global_load_dwordx4 v[0:3], v27, s[56:57]
	global_load_dwordx4 v[4:7], v27, s[58:59]
	s_waitcnt vmcnt(2)
	v_lshlrev_b32_e32 v8, 16, v30
	v_and_b32_e32 v9, 0xffff0000, v30
	s_waitcnt lgkmcnt(1)
	v_pk_add_f32 v[8:9], v[8:9], v[16:17] op_sel_hi:[1,0] neg_lo:[0,1] neg_hi:[0,1]
	v_lshlrev_b32_e32 v30, 16, v31
	s_waitcnt lgkmcnt(0)
	v_pk_mul_f32 v[8:9], v[22:23], v[8:9] op_sel_hi:[0,1]
	v_and_b32_e32 v31, 0xffff0000, v31
	v_pk_add_f32 v[30:31], v[30:31], v[16:17] op_sel_hi:[1,0] neg_lo:[0,1] neg_hi:[0,1]
	s_waitcnt vmcnt(0)
	v_pk_fma_f32 v[34:35], v[0:1], v[8:9], v[4:5]
	v_lshlrev_b32_e32 v8, 16, v32
	v_and_b32_e32 v9, 0xffff0000, v32
	v_pk_add_f32 v[8:9], v[8:9], v[16:17] op_sel_hi:[1,0] neg_lo:[0,1] neg_hi:[0,1]
	v_lshlrev_b32_e32 v32, 16, v33
	v_pk_mul_f32 v[38:39], v[22:23], v[8:9] op_sel_hi:[0,1]
	global_load_dwordx4 v[8:11], v27, s[56:57] offset:16
	global_load_dwordx4 v[12:15], v27, s[58:59] offset:16
	v_and_b32_e32 v33, 0xffff0000, v33
	v_pk_add_f32 v[16:17], v[32:33], v[16:17] op_sel_hi:[1,0] neg_lo:[0,1] neg_hi:[0,1]
	v_pk_mul_f32 v[30:31], v[22:23], v[30:31] op_sel_hi:[0,1]
	v_pk_mul_f32 v[16:17], v[22:23], v[16:17] op_sel_hi:[0,1]
	v_pk_fma_f32 v[30:31], v[2:3], v[30:31], v[6:7]
	s_waitcnt vmcnt(0)
	v_pk_fma_f32 v[40:41], v[8:9], v[38:39], v[12:13]
	v_pk_fma_f32 v[16:17], v[10:11], v[16:17], v[14:15]
	v_cvt_pk_bf16_f32 v40, v40, v41
	v_cvt_pk_bf16_f32 v41, v16, v17
	v_lshlrev_b32_e32 v17, 1, v20
	v_and_or_b32 v17, v17, 8, v21
	v_lshrrev_b32_e32 v17, 1, v17
	v_lshlrev_b32_e32 v16, 8, v20
	v_or_b32_e32 v17, v17, v24
	v_and_b32_e32 v16, 0xffffc000, v16
	v_lshl_or_b32 v17, v17, 9, v28
	v_cvt_pk_bf16_f32 v38, v34, v35
	v_cvt_pk_bf16_f32 v39, v30, v31
	v_add3_u32 v16, 0, v16, v17
	v_add_u32_e32 v32, 0x8800, v16
	ds_write_b128 v16, v[38:41] offset:34816
	v_add_u32_e32 v16, s25, v29
	v_mad_i64_i32 v[16:17], s[26:27], v16, s69, v[66:67]
	v_lshl_add_u64 v[16:17], v[16:17], 0, s[60:61]
	v_lshl_add_u64 v[22:23], v[16:17], 0, v[64:65]
	global_load_dwordx4 v[38:41], v[22:23], off nt
	v_lshlrev_b32_e32 v23, 2, v29
	v_add_u32_e32 v33, s3, v23
	ds_read_b32 v22, v33
	v_add_u32_e32 v34, s8, v23
	ds_read_b32 v30, v34
	s_waitcnt vmcnt(0)
	v_lshlrev_b32_e32 v42, 16, v38
	v_and_b32_e32 v43, 0xffff0000, v38
	v_lshlrev_b32_e32 v38, 16, v39
	v_and_b32_e32 v39, 0xffff0000, v39
	s_waitcnt lgkmcnt(1)
	v_pk_add_f32 v[38:39], v[38:39], v[22:23] op_sel_hi:[1,0] neg_lo:[0,1] neg_hi:[0,1]
	v_lshlrev_b32_e32 v44, 16, v40
	s_waitcnt lgkmcnt(0)
	v_pk_mul_f32 v[38:39], v[30:31], v[38:39] op_sel_hi:[0,1]
	v_and_b32_e32 v45, 0xffff0000, v40
	v_pk_fma_f32 v[46:47], v[2:3], v[38:39], v[6:7]
	v_lshlrev_b32_e32 v38, 16, v41
	v_and_b32_e32 v39, 0xffff0000, v41
	v_pk_add_f32 v[42:43], v[42:43], v[22:23] op_sel_hi:[1,0] neg_lo:[0,1] neg_hi:[0,1]
	v_pk_add_f32 v[44:45], v[44:45], v[22:23] op_sel_hi:[1,0] neg_lo:[0,1] neg_hi:[0,1]
	v_pk_add_f32 v[22:23], v[38:39], v[22:23] op_sel_hi:[1,0] neg_lo:[0,1] neg_hi:[0,1]
	v_pk_mul_f32 v[42:43], v[30:31], v[42:43] op_sel_hi:[0,1]
	v_pk_mul_f32 v[22:23], v[30:31], v[22:23] op_sel_hi:[0,1]
	v_pk_fma_f32 v[22:23], v[10:11], v[22:23], v[14:15]
	v_pk_mul_f32 v[44:45], v[30:31], v[44:45] op_sel_hi:[0,1]
	v_cvt_pk_bf16_f32 v41, v22, v23
	v_lshlrev_b32_e32 v22, 8, v29
	v_and_b32_e32 v23, 48, v29
	v_lshlrev_b32_e32 v29, 1, v29
	v_and_or_b32 v23, v29, 8, v23
	v_lshrrev_b32_e32 v23, 1, v23
	v_or_b32_e32 v23, v23, v24
	v_pk_fma_f32 v[42:43], v[0:1], v[42:43], v[4:5]
	v_pk_fma_f32 v[44:45], v[8:9], v[44:45], v[12:13]
	v_and_b32_e32 v22, 0xffffc000, v22
	v_lshl_or_b32 v23, v23, 9, v28
	v_cvt_pk_bf16_f32 v38, v42, v43
	v_cvt_pk_bf16_f32 v39, v46, v47
	v_cvt_pk_bf16_f32 v40, v44, v45
	v_add3_u32 v22, 0, v22, v23
	v_add_u32_e32 v29, 64, v20
	v_add_u32_e32 v35, 0x8800, v22
	ds_write_b128 v22, v[38:41] offset:34816
	v_add_u32_e32 v22, s25, v29
	v_mad_i64_i32 v[22:23], s[26:27], v22, s69, v[66:67]
	v_lshl_add_u64 v[22:23], v[22:23], 0, s[60:61]
	v_lshl_add_u64 v[30:31], v[22:23], 0, v[64:65]
	global_load_dwordx4 v[40:43], v[30:31], off nt
	v_lshlrev_b32_e32 v31, 2, v29
	v_add_u32_e32 v38, s3, v31
	ds_read_b32 v30, v38
	v_add_u32_e32 v39, s8, v31
	ds_read_b32 v44, v39
	s_waitcnt vmcnt(0)
	v_lshlrev_b32_e32 v46, 16, v40
	v_and_b32_e32 v47, 0xffff0000, v40
	v_lshlrev_b32_e32 v40, 16, v41
	v_and_b32_e32 v41, 0xffff0000, v41
	s_waitcnt lgkmcnt(1)
	v_pk_add_f32 v[40:41], v[40:41], v[30:31] op_sel_hi:[1,0] neg_lo:[0,1] neg_hi:[0,1]
	v_lshlrev_b32_e32 v48, 16, v42
	s_waitcnt lgkmcnt(0)
	v_pk_mul_f32 v[40:41], v[44:45], v[40:41] op_sel_hi:[0,1]
	v_and_b32_e32 v49, 0xffff0000, v42
	v_pk_fma_f32 v[50:51], v[2:3], v[40:41], v[6:7]
	v_lshlrev_b32_e32 v40, 16, v43
	v_and_b32_e32 v41, 0xffff0000, v43
	v_pk_add_f32 v[46:47], v[46:47], v[30:31] op_sel_hi:[1,0] neg_lo:[0,1] neg_hi:[0,1]
	v_pk_add_f32 v[48:49], v[48:49], v[30:31] op_sel_hi:[1,0] neg_lo:[0,1] neg_hi:[0,1]
	v_pk_add_f32 v[30:31], v[40:41], v[30:31] op_sel_hi:[1,0] neg_lo:[0,1] neg_hi:[0,1]
	v_pk_mul_f32 v[46:47], v[44:45], v[46:47] op_sel_hi:[0,1]
	v_pk_mul_f32 v[30:31], v[44:45], v[30:31] op_sel_hi:[0,1]
	v_pk_fma_f32 v[30:31], v[10:11], v[30:31], v[14:15]
	v_pk_mul_f32 v[48:49], v[44:45], v[48:49] op_sel_hi:[0,1]
	v_cvt_pk_bf16_f32 v43, v30, v31
	v_lshlrev_b32_e32 v30, 8, v29
	v_lshlrev_b32_e32 v29, 1, v29
	v_and_or_b32 v21, v29, 8, v21
	v_lshrrev_b32_e32 v21, 1, v21
	v_or_b32_e32 v21, v21, v24
	v_pk_fma_f32 v[46:47], v[0:1], v[46:47], v[4:5]
	v_pk_fma_f32 v[48:49], v[8:9], v[48:49], v[12:13]
	v_and_b32_e32 v30, 0xffffc000, v30
	v_lshl_or_b32 v21, v21, 9, v28
	v_add_u32_e32 v45, 0x60, v20
	v_cvt_pk_bf16_f32 v40, v46, v47
	v_cvt_pk_bf16_f32 v41, v50, v51
	v_cvt_pk_bf16_f32 v42, v48, v49
	v_add3_u32 v21, 0, v30, v21
	v_add_u32_e32 v20, s25, v45
	v_add_u32_e32 v31, 0x8800, v21
	ds_write_b128 v21, v[40:43] offset:34816
	v_mad_i64_i32 v[20:21], s[26:27], v20, s69, v[66:67]
	v_lshl_add_u64 v[20:21], v[20:21], 0, s[60:61]
	v_lshl_add_u64 v[40:41], v[20:21], 0, v[64:65]
	global_load_dwordx4 v[40:43], v[40:41], off nt
	v_lshlrev_b32_e32 v30, 2, v45
	v_add_u32_e32 v29, s3, v30
	ds_read_b32 v44, v29
	v_add_u32_e32 v30, s8, v30
	ds_read_b32 v46, v30
	v_or_b32_e32 v64, 0x100, v64
	s_waitcnt vmcnt(0)
	v_lshlrev_b32_e32 v48, 16, v40
	v_and_b32_e32 v49, 0xffff0000, v40
	s_waitcnt lgkmcnt(1)
	v_pk_add_f32 v[48:49], v[48:49], v[44:45] op_sel_hi:[1,0] neg_lo:[0,1] neg_hi:[0,1]
	s_waitcnt lgkmcnt(0)
	v_pk_mul_f32 v[48:49], v[46:47], v[48:49] op_sel_hi:[0,1]
	v_pk_fma_f32 v[0:1], v[0:1], v[48:49], v[4:5]
	v_lshlrev_b32_e32 v4, 16, v42
	v_and_b32_e32 v5, 0xffff0000, v42
	v_pk_add_f32 v[4:5], v[4:5], v[44:45] op_sel_hi:[1,0] neg_lo:[0,1] neg_hi:[0,1]
	v_cvt_pk_bf16_f32 v0, v0, v1
	v_pk_mul_f32 v[4:5], v[46:47], v[4:5] op_sel_hi:[0,1]
	v_pk_fma_f32 v[4:5], v[8:9], v[4:5], v[12:13]
	v_lshlrev_b32_e32 v8, 16, v41
	v_and_b32_e32 v9, 0xffff0000, v41
	v_pk_add_f32 v[8:9], v[8:9], v[44:45] op_sel_hi:[1,0] neg_lo:[0,1] neg_hi:[0,1]
	s_nop 0
	v_pk_mul_f32 v[8:9], v[46:47], v[8:9] op_sel_hi:[0,1]
	v_pk_fma_f32 v[2:3], v[2:3], v[8:9], v[6:7]
	v_lshlrev_b32_e32 v6, 16, v43
	v_and_b32_e32 v7, 0xffff0000, v43
	v_pk_add_f32 v[6:7], v[6:7], v[44:45] op_sel_hi:[1,0] neg_lo:[0,1] neg_hi:[0,1]
	v_cvt_pk_bf16_f32 v1, v2, v3
	v_pk_mul_f32 v[6:7], v[46:47], v[6:7] op_sel_hi:[0,1]
	v_pk_fma_f32 v[6:7], v[10:11], v[6:7], v[14:15]
	v_cvt_pk_bf16_f32 v2, v4, v5
	v_cvt_pk_bf16_f32 v3, v6, v7
	v_and_b32_e32 v5, 48, v45
	v_lshlrev_b32_e32 v6, 1, v45
	v_and_or_b32 v5, v6, 8, v5
	v_lshrrev_b32_e32 v5, 1, v5
	v_lshlrev_b32_e32 v4, 8, v45
	v_or_b32_e32 v5, v5, v24
	v_and_b32_e32 v4, 0xffffc000, v4
	v_lshl_or_b32 v5, v5, 9, v28
	v_add3_u32 v4, 0, v4, v5
	ds_write_b128 v4, v[0:3] offset:34816
	v_lshl_add_u64 v[0:1], v[18:19], 0, v[64:65]
	global_load_dwordx4 v[12:15], v[0:1], off nt
	v_add_u32_e32 v28, 0x8800, v4
	ds_read_b32 v18, v36
	ds_read_b32 v24, v37
	global_load_dwordx4 v[0:3], v27, s[56:57] offset:512
	global_load_dwordx4 v[8:11], v27, s[56:57] offset:528
	global_load_dwordx4 v[4:7], v27, s[58:59] offset:512
	global_load_dwordx4 v[40:43], v27, s[58:59] offset:528
	s_waitcnt vmcnt(4)
	v_lshlrev_b32_e32 v36, 16, v12
	v_and_b32_e32 v37, 0xffff0000, v12
	v_lshlrev_b32_e32 v12, 16, v13
	v_and_b32_e32 v13, 0xffff0000, v13
	s_waitcnt lgkmcnt(1)
	v_pk_add_f32 v[12:13], v[12:13], v[18:19] op_sel_hi:[1,0] neg_lo:[0,1] neg_hi:[0,1]
	v_lshlrev_b32_e32 v44, 16, v14
	s_waitcnt lgkmcnt(0)
	v_pk_mul_f32 v[12:13], v[24:25], v[12:13] op_sel_hi:[0,1]
	v_and_b32_e32 v45, 0xffff0000, v14
	s_waitcnt vmcnt(1)
	v_pk_fma_f32 v[46:47], v[2:3], v[12:13], v[6:7]
	v_lshlrev_b32_e32 v12, 16, v15
	v_and_b32_e32 v13, 0xffff0000, v15
	v_pk_add_f32 v[36:37], v[36:37], v[18:19] op_sel_hi:[1,0] neg_lo:[0,1] neg_hi:[0,1]
	v_pk_add_f32 v[44:45], v[44:45], v[18:19] op_sel_hi:[1,0] neg_lo:[0,1] neg_hi:[0,1]
	v_pk_add_f32 v[12:13], v[12:13], v[18:19] op_sel_hi:[1,0] neg_lo:[0,1] neg_hi:[0,1]
	v_pk_mul_f32 v[36:37], v[24:25], v[36:37] op_sel_hi:[0,1]
	v_pk_mul_f32 v[44:45], v[24:25], v[44:45] op_sel_hi:[0,1]
	v_pk_mul_f32 v[12:13], v[24:25], v[12:13] op_sel_hi:[0,1]
	v_pk_fma_f32 v[36:37], v[0:1], v[36:37], v[4:5]
	s_waitcnt vmcnt(0)
	v_pk_fma_f32 v[44:45], v[8:9], v[44:45], v[40:41]
	v_pk_fma_f32 v[18:19], v[10:11], v[12:13], v[42:43]
	v_cvt_pk_bf16_f32 v12, v36, v37
	v_cvt_pk_bf16_f32 v13, v46, v47
	v_cvt_pk_bf16_f32 v14, v44, v45
	v_cvt_pk_bf16_f32 v15, v18, v19
	ds_write_b128 v32, v[12:15] offset:32768
	v_lshl_add_u64 v[12:13], v[16:17], 0, v[64:65]
	global_load_dwordx4 v[12:15], v[12:13], off nt
	ds_read_b32 v16, v33
	ds_read_b32 v18, v34
	s_waitcnt vmcnt(0)
	v_lshlrev_b32_e32 v36, 16, v14
	v_and_b32_e32 v37, 0xffff0000, v14
	s_waitcnt lgkmcnt(1)
	v_pk_add_f32 v[36:37], v[36:37], v[16:17] op_sel_hi:[1,0] neg_lo:[0,1] neg_hi:[0,1]
	v_lshlrev_b32_e32 v32, 16, v12
	s_waitcnt lgkmcnt(0)
	v_pk_mul_f32 v[36:37], v[18:19], v[36:37] op_sel_hi:[0,1]
	v_pk_fma_f32 v[36:37], v[8:9], v[36:37], v[40:41]
	v_lshlrev_b32_e32 v8, 16, v13
	v_and_b32_e32 v9, 0xffff0000, v13
	v_pk_add_f32 v[8:9], v[8:9], v[16:17] op_sel_hi:[1,0] neg_lo:[0,1] neg_hi:[0,1]
	v_and_b32_e32 v33, 0xffff0000, v12
	v_pk_mul_f32 v[8:9], v[18:19], v[8:9] op_sel_hi:[0,1]
	v_pk_fma_f32 v[12:13], v[2:3], v[8:9], v[6:7]
	v_lshlrev_b32_e32 v8, 16, v15
	v_and_b32_e32 v9, 0xffff0000, v15
	v_pk_add_f32 v[32:33], v[32:33], v[16:17] op_sel_hi:[1,0] neg_lo:[0,1] neg_hi:[0,1]
	v_pk_add_f32 v[8:9], v[8:9], v[16:17] op_sel_hi:[1,0] neg_lo:[0,1] neg_hi:[0,1]
	v_pk_mul_f32 v[32:33], v[18:19], v[32:33] op_sel_hi:[0,1]
	v_pk_mul_f32 v[8:9], v[18:19], v[8:9] op_sel_hi:[0,1]
	v_pk_fma_f32 v[32:33], v[0:1], v[32:33], v[4:5]
	v_pk_fma_f32 v[14:15], v[10:11], v[8:9], v[42:43]
	v_cvt_pk_bf16_f32 v8, v32, v33
	v_cvt_pk_bf16_f32 v9, v12, v13
	v_cvt_pk_bf16_f32 v10, v36, v37
	v_cvt_pk_bf16_f32 v11, v14, v15
	ds_write_b128 v35, v[8:11] offset:32768
	v_lshl_add_u64 v[8:9], v[22:23], 0, v[64:65]
	global_load_dwordx4 v[12:15], v[8:9], off nt
	ds_read_b32 v22, v38
	ds_read_b32 v24, v39
	global_load_dwordx4 v[8:11], v27, s[56:57] offset:528
	global_load_dwordx4 v[16:19], v27, s[58:59] offset:528
	s_waitcnt vmcnt(2)
	v_lshlrev_b32_e32 v32, 16, v12
	v_and_b32_e32 v33, 0xffff0000, v12
	v_lshlrev_b32_e32 v12, 16, v13
	v_and_b32_e32 v13, 0xffff0000, v13
	s_waitcnt lgkmcnt(1)
	v_pk_add_f32 v[12:13], v[12:13], v[22:23] op_sel_hi:[1,0] neg_lo:[0,1] neg_hi:[0,1]
	v_lshlrev_b32_e32 v34, 16, v14
	s_waitcnt lgkmcnt(0)
	v_pk_mul_f32 v[12:13], v[24:25], v[12:13] op_sel_hi:[0,1]
	v_and_b32_e32 v35, 0xffff0000, v14
	v_pk_fma_f32 v[36:37], v[2:3], v[12:13], v[6:7]
	v_lshlrev_b32_e32 v12, 16, v15
	v_and_b32_e32 v13, 0xffff0000, v15
	v_pk_add_f32 v[32:33], v[32:33], v[22:23] op_sel_hi:[1,0] neg_lo:[0,1] neg_hi:[0,1]
	v_pk_add_f32 v[34:35], v[34:35], v[22:23] op_sel_hi:[1,0] neg_lo:[0,1] neg_hi:[0,1]
	v_pk_add_f32 v[12:13], v[12:13], v[22:23] op_sel_hi:[1,0] neg_lo:[0,1] neg_hi:[0,1]
	v_pk_mul_f32 v[32:33], v[24:25], v[32:33] op_sel_hi:[0,1]
	v_pk_mul_f32 v[34:35], v[24:25], v[34:35] op_sel_hi:[0,1]
	v_pk_mul_f32 v[12:13], v[24:25], v[12:13] op_sel_hi:[0,1]
	v_pk_fma_f32 v[32:33], v[0:1], v[32:33], v[4:5]
	s_waitcnt vmcnt(0)
	v_pk_fma_f32 v[34:35], v[8:9], v[34:35], v[16:17]
	v_pk_fma_f32 v[22:23], v[10:11], v[12:13], v[18:19]
	v_cvt_pk_bf16_f32 v12, v32, v33
	v_cvt_pk_bf16_f32 v13, v36, v37
	v_cvt_pk_bf16_f32 v14, v34, v35
	v_cvt_pk_bf16_f32 v15, v22, v23
	ds_write_b128 v31, v[12:15] offset:32768
	v_lshl_add_u64 v[12:13], v[20:21], 0, v[64:65]
	global_load_dwordx4 v[12:15], v[12:13], off nt
	ds_read_b32 v20, v29
	ds_read_b32 v22, v30
	v_and_b32_e32 v64, 31, v68
	s_waitcnt vmcnt(0)
	v_lshlrev_b32_e32 v30, 16, v12
	v_and_b32_e32 v31, 0xffff0000, v12
	s_waitcnt lgkmcnt(1)
	v_pk_add_f32 v[30:31], v[30:31], v[20:21] op_sel_hi:[1,0] neg_lo:[0,1] neg_hi:[0,1]
	s_waitcnt lgkmcnt(0)
	v_pk_mul_f32 v[30:31], v[22:23], v[30:31] op_sel_hi:[0,1]
	v_pk_fma_f32 v[0:1], v[0:1], v[30:31], v[4:5]
	v_lshlrev_b32_e32 v4, 16, v14
	v_and_b32_e32 v5, 0xffff0000, v14
	v_pk_add_f32 v[4:5], v[4:5], v[20:21] op_sel_hi:[1,0] neg_lo:[0,1] neg_hi:[0,1]
	v_cvt_pk_bf16_f32 v0, v0, v1
	v_pk_mul_f32 v[4:5], v[22:23], v[4:5] op_sel_hi:[0,1]
	v_pk_fma_f32 v[4:5], v[8:9], v[4:5], v[16:17]
	v_lshlrev_b32_e32 v8, 16, v13
	v_and_b32_e32 v9, 0xffff0000, v13
	v_pk_add_f32 v[8:9], v[8:9], v[20:21] op_sel_hi:[1,0] neg_lo:[0,1] neg_hi:[0,1]
	s_nop 0
	v_pk_mul_f32 v[8:9], v[22:23], v[8:9] op_sel_hi:[0,1]
	v_pk_fma_f32 v[2:3], v[2:3], v[8:9], v[6:7]
	v_lshlrev_b32_e32 v6, 16, v15
	v_and_b32_e32 v7, 0xffff0000, v15
	v_pk_add_f32 v[6:7], v[6:7], v[20:21] op_sel_hi:[1,0] neg_lo:[0,1] neg_hi:[0,1]
	v_cvt_pk_bf16_f32 v1, v2, v3
	v_pk_mul_f32 v[6:7], v[22:23], v[6:7] op_sel_hi:[0,1]
	v_pk_fma_f32 v[6:7], v[10:11], v[6:7], v[18:19]
	v_cvt_pk_bf16_f32 v2, v4, v5
	v_cvt_pk_bf16_f32 v3, v6, v7
	ds_write_b128 v28, v[0:3] offset:32768
	v_or_b32_e32 v0, s10, v64
	v_lshlrev_b32_e32 v2, 3, v25
	v_and_b32_e32 v3, 0xc0, v26
	v_lshlrev_b32_e32 v4, 1, v68
	v_mul_u32_u24_e32 v0, 0x110, v0
	v_lshlrev_b32_e32 v1, 4, v102
	v_and_or_b32 v3, v2, 24, v3
	v_and_b32_e32 v4, 32, v4
	v_and_b32_e32 v2, 0x100, v2
	v_or3_b32 v94, v3, v4, v2
	v_add3_u32 v95, 0, v0, v1
	s_waitcnt lgkmcnt(0)
	s_barrier
	ds_read_b128 v[48:51], v95
	ds_read_b128 v[70:73], v95 offset:32
	ds_read_b128 v[74:77], v95 offset:64
	ds_read_b128 v[78:81], v95 offset:96
	v_add_u32_e32 v96, s11, v94
	ds_read_b64_tr_b16 v[0:1], v96 offset:0
	ds_read_b64_tr_b16 v[2:3], v96 offset:0x800
	ds_read_b64_tr_b16 v[16:17], v96 offset:0x1000
	ds_read_b64_tr_b16 v[18:19], v96 offset:0x1800
	ds_read_b64_tr_b16 v[20:21], v96 offset:0x2000
	ds_read_b64_tr_b16 v[22:23], v96 offset:0x2800
	ds_read_b64_tr_b16 v[24:25], v96 offset:0x3000
	ds_read_b64_tr_b16 v[26:27], v96 offset:0x3800
	s_waitcnt lgkmcnt(0)
	s_waitcnt lgkmcnt(3)
	v_mfma_f32_32x32x16_bf16 v[0:15], v[48:51], v[0:3], 0
	s_waitcnt lgkmcnt(2)
	v_mfma_f32_32x32x16_bf16 v[0:15], v[70:73], v[16:19], v[0:15]
	ds_read_b64_tr_b16 v[16:17], v96 offset:0x200
	ds_read_b64_tr_b16 v[18:19], v96 offset:0xa00
	ds_read_b64_tr_b16 v[32:33], v96 offset:0x1200
	ds_read_b64_tr_b16 v[34:35], v96 offset:0x1a00
	ds_read_b64_tr_b16 v[36:37], v96 offset:0x2200
	ds_read_b64_tr_b16 v[38:39], v96 offset:0x2a00
	ds_read_b64_tr_b16 v[40:41], v96 offset:0x3200
	s_waitcnt lgkmcnt(1)
	v_mfma_f32_32x32x16_bf16 v[0:15], v[74:77], v[20:23], v[0:15]
	ds_read_b64_tr_b16 v[42:43], v96 offset:0x3a00
	s_waitcnt lgkmcnt(0)
	s_waitcnt lgkmcnt(0)
	v_mfma_f32_32x32x16_bf16 v[0:15], v[78:81], v[24:27], v[0:15]
	v_mfma_f32_32x32x16_bf16 v[16:31], v[48:51], v[16:19], 0
	v_mfma_f32_32x32x16_bf16 v[16:31], v[70:73], v[32:35], v[16:31]
	ds_read_b64_tr_b16 v[32:33], v96 offset:0x400
	ds_read_b64_tr_b16 v[34:35], v96 offset:0xc00
	ds_read_b64_tr_b16 v[52:53], v96 offset:0x1400
	ds_read_b64_tr_b16 v[54:55], v96 offset:0x1c00
	ds_read_b64_tr_b16 v[56:57], v96 offset:0x2400
	ds_read_b64_tr_b16 v[58:59], v96 offset:0x2c00
	ds_read_b64_tr_b16 v[60:61], v96 offset:0x3400
	v_mfma_f32_32x32x16_bf16 v[16:31], v[74:77], v[36:39], v[16:31]
	ds_read_b64_tr_b16 v[62:63], v96 offset:0x3c00
	s_waitcnt lgkmcnt(0)
	v_mfma_f32_32x32x16_bf16 v[16:31], v[78:81], v[40:43], v[16:31]
	v_mfma_f32_32x32x16_bf16 v[32:47], v[48:51], v[32:35], 0
	v_mfma_f32_32x32x16_bf16 v[32:47], v[70:73], v[52:55], v[32:47]
	ds_read_b64_tr_b16 v[52:53], v96 offset:0x600
	ds_read_b64_tr_b16 v[54:55], v96 offset:0xe00
	ds_read_b64_tr_b16 v[82:83], v96 offset:0x1600
	ds_read_b64_tr_b16 v[84:85], v96 offset:0x1e00
	ds_read_b64_tr_b16 v[86:87], v96 offset:0x2600
	ds_read_b64_tr_b16 v[88:89], v96 offset:0x2e00
	ds_read_b64_tr_b16 v[90:91], v96 offset:0x3600
	v_mfma_f32_32x32x16_bf16 v[32:47], v[74:77], v[56:59], v[32:47]
	ds_read_b64_tr_b16 v[92:93], v96 offset:0x3e00
	s_waitcnt lgkmcnt(0)
	v_mfma_f32_32x32x16_bf16 v[32:47], v[78:81], v[60:63], v[32:47]
	v_mfma_f32_32x32x16_bf16 v[48:63], v[48:51], v[52:55], 0
	v_add_u32_e32 v103, s12, v94
	v_mfma_f32_32x32x16_bf16 v[48:63], v[70:73], v[82:85], v[48:63]
	v_mfma_f32_32x32x16_bf16 v[48:63], v[74:77], v[86:89], v[48:63]
	v_mfma_f32_32x32x16_bf16 v[48:63], v[78:81], v[90:93], v[48:63]
	ds_read_b128 v[70:73], v95 offset:128
	ds_read_b128 v[74:77], v95 offset:160
	ds_read_b128 v[78:81], v95 offset:192
	ds_read_b128 v[82:85], v95 offset:224
	ds_read_b64_tr_b16 v[86:87], v103 offset:0
	ds_read_b64_tr_b16 v[88:89], v103 offset:0x800
	ds_read_b64_tr_b16 v[90:91], v103 offset:0x1000
	ds_read_b64_tr_b16 v[92:93], v103 offset:0x1800
	ds_read_b64_tr_b16 v[94:95], v103 offset:0x2000
	ds_read_b64_tr_b16 v[96:97], v103 offset:0x2800
	ds_read_b64_tr_b16 v[98:99], v103 offset:0x3000
	ds_read_b64_tr_b16 v[100:101], v103 offset:0x3800
	s_waitcnt lgkmcnt(0)
	s_waitcnt lgkmcnt(3)
	v_mfma_f32_32x32x16_bf16 v[0:15], v[70:73], v[86:89], v[0:15]
	ds_read_b64_tr_b16 v[86:87], v103 offset:0x200
	ds_read_b64_tr_b16 v[88:89], v103 offset:0xa00
	s_waitcnt lgkmcnt(2)
	v_mfma_f32_32x32x16_bf16 v[0:15], v[74:77], v[90:93], v[0:15]
	ds_read_b64_tr_b16 v[90:91], v103 offset:0x1200
	ds_read_b64_tr_b16 v[92:93], v103 offset:0x1a00
	s_waitcnt lgkmcnt(1)
	v_mfma_f32_32x32x16_bf16 v[0:15], v[78:81], v[94:97], v[0:15]
	ds_read_b64_tr_b16 v[94:95], v103 offset:0x2200
	ds_read_b64_tr_b16 v[96:97], v103 offset:0x2a00
	s_waitcnt lgkmcnt(0)
	v_mfma_f32_32x32x16_bf16 v[0:15], v[82:85], v[98:101], v[0:15]
	ds_read_b64_tr_b16 v[98:99], v103 offset:0x3200
	ds_read_b64_tr_b16 v[100:101], v103 offset:0x3a00
	s_waitcnt lgkmcnt(0)
	v_mfma_f32_32x32x16_bf16 v[16:31], v[70:73], v[86:89], v[16:31]
	ds_read_b64_tr_b16 v[86:87], v103 offset:0x400
	ds_read_b64_tr_b16 v[88:89], v103 offset:0xc00
	v_mfma_f32_32x32x16_bf16 v[16:31], v[74:77], v[90:93], v[16:31]
	ds_read_b64_tr_b16 v[90:91], v103 offset:0x1400
	ds_read_b64_tr_b16 v[92:93], v103 offset:0x1c00
	v_mfma_f32_32x32x16_bf16 v[16:31], v[78:81], v[94:97], v[16:31]
	ds_read_b64_tr_b16 v[94:95], v103 offset:0x2400
	ds_read_b64_tr_b16 v[96:97], v103 offset:0x2c00
	v_mfma_f32_32x32x16_bf16 v[16:31], v[82:85], v[98:101], v[16:31]
	ds_read_b64_tr_b16 v[98:99], v103 offset:0x3400
	ds_read_b64_tr_b16 v[100:101], v103 offset:0x3c00
	s_waitcnt lgkmcnt(0)
	v_mfma_f32_32x32x16_bf16 v[32:47], v[70:73], v[86:89], v[32:47]
	ds_read_b64_tr_b16 v[86:87], v103 offset:0x600
	ds_read_b64_tr_b16 v[88:89], v103 offset:0xe00
	v_mfma_f32_32x32x16_bf16 v[32:47], v[74:77], v[90:93], v[32:47]
	ds_read_b64_tr_b16 v[90:91], v103 offset:0x1600
	ds_read_b64_tr_b16 v[92:93], v103 offset:0x1e00
	v_mfma_f32_32x32x16_bf16 v[32:47], v[78:81], v[94:97], v[32:47]
	ds_read_b64_tr_b16 v[94:95], v103 offset:0x2600
	ds_read_b64_tr_b16 v[96:97], v103 offset:0x2e00
	v_mfma_f32_32x32x16_bf16 v[32:47], v[82:85], v[98:101], v[32:47]
	ds_read_b64_tr_b16 v[98:99], v103 offset:0x3600
	ds_read_b64_tr_b16 v[100:101], v103 offset:0x3e00
	s_waitcnt lgkmcnt(0)
	v_mfma_f32_32x32x16_bf16 v[48:63], v[70:73], v[86:89], v[48:63]
	v_mul_u32_u24_e32 v70, 0x840, v102
	v_lshlrev_b32_e32 v64, 2, v64
	v_add3_u32 v64, s13, v70, v64
	s_barrier
	s_add_i32 s2, s2, s14
	v_mfma_f32_32x32x16_bf16 v[48:63], v[74:77], v[90:93], v[48:63]
	s_movk_i32 s8, 0x2000
	v_mfma_f32_32x32x16_bf16 v[48:63], v[78:81], v[94:97], v[48:63]
	v_mfma_f32_32x32x16_bf16 v[48:63], v[82:85], v[98:101], v[48:63]
	ds_write2_b32 v64, v0, v16 offset1:32
	s_nop 10
	ds_write2_b32 v64, v32, v48 offset0:64 offset1:96
	ds_write2_b32 v64, v1, v17 offset0:132 offset1:164
	ds_write2_b32 v64, v33, v49 offset0:196 offset1:228
	v_add_u32_e32 v0, 0x400, v64
	ds_write2_b32 v0, v2, v18 offset0:8 offset1:40
	ds_write2_b32 v0, v34, v50 offset0:72 offset1:104
	ds_write2_b32 v0, v3, v19 offset0:140 offset1:172
	ds_write2_b32 v0, v35, v51 offset0:204 offset1:236
	v_add_u32_e32 v0, 0x1000, v64
	ds_write2_b32 v0, v4, v20 offset0:32 offset1:64
	ds_write2_b32 v0, v36, v52 offset0:96 offset1:128
	ds_write2_b32 v0, v5, v21 offset0:164 offset1:196
	v_add_u32_e32 v0, 0x1200, v64
	ds_write2_b32 v0, v37, v53 offset0:100 offset1:132
	v_add_u32_e32 v0, 0x1400, v64
	ds_write2_b32 v0, v6, v22 offset0:40 offset1:72
	ds_write2_b32 v0, v38, v54 offset0:104 offset1:136
	ds_write2_b32 v0, v7, v23 offset0:172 offset1:204
	v_add_u32_e32 v0, 0x1600, v64
	ds_write2_b32 v0, v39, v55 offset0:108 offset1:140
	v_add_u32_e32 v0, 0x2000, v64
	ds_write2_b32 v0, v8, v24 offset0:64 offset1:96
	ds_write2_b32 v0, v40, v56 offset0:128 offset1:160
	ds_write2_b32 v0, v9, v25 offset0:196 offset1:228
	v_add_u32_e32 v0, 0x2400, v64
	ds_write2_b32 v0, v41, v57 offset0:4 offset1:36
	ds_write2_b32 v0, v10, v26 offset0:72 offset1:104
	ds_write2_b32 v0, v42, v58 offset0:136 offset1:168
	ds_write2_b32 v0, v11, v27 offset0:204 offset1:236
	v_add_u32_e32 v0, 0x2800, v64
	ds_write2_b32 v0, v43, v59 offset0:12 offset1:44
	v_add_u32_e32 v0, 0x3000, v64
	ds_write2_b32 v0, v12, v28 offset0:96 offset1:128
	ds_write2_b32 v0, v44, v60 offset0:160 offset1:192
	v_add_u32_e32 v0, 0x3200, v64
	ds_write2_b32 v0, v13, v29 offset0:100 offset1:132
	v_add_u32_e32 v0, 0x3400, v64
	ds_write2_b32 v0, v45, v61 offset0:36 offset1:68
	ds_write2_b32 v0, v14, v30 offset0:104 offset1:136
	ds_write2_b32 v0, v46, v62 offset0:168 offset1:200
	v_add_u32_e32 v0, 0x3600, v64
	ds_write2_b32 v0, v15, v31 offset0:108 offset1:140
	v_add_u32_e32 v0, 0x3800, v64
	v_bfe_u32 v23, v68, 4, 2
	ds_write2_b32 v0, v47, v63 offset0:44 offset1:76
	v_or_b32_e32 v0, s2, v69
	v_or_b32_e32 v22, s10, v23
	v_ashrrev_i32_e32 v1, 31, v0
	v_or_b32_e32 v20, s25, v22
	v_lshlrev_b32_e32 v2, 2, v69
	s_lshl_b64 s[2:3], s[6:7], 9
	v_lshlrev_b64 v[18:19], 1, v[0:1]
	v_mul_u32_u24_e32 v0, 0x210, v23
	v_mad_i64_i32 v[8:9], s[6:7], v20, s69, v[66:67]
	v_add3_u32 v24, s13, v2, v0
	v_lshl_add_u64 v[8:9], v[8:9], 0, v[18:19]
	s_add_u32 s6, s84, s2
	ds_read_b128 v[4:7], v24
	ds_read_b128 v[0:3], v24 offset:16
	global_load_dwordx4 v[12:15], v[8:9], off nt
	v_add_co_u32_e32 v8, vcc, s8, v8
	s_addc_u32 s7, s85, s3
	v_lshlrev_b32_e32 v22, 2, v22
	v_addc_co_u32_e32 v9, vcc, 0, v9, vcc
	global_load_dword v22, v22, s[6:7]
	v_ashrrev_i32_e32 v21, 31, v20
	global_load_dwordx4 v[8:11], v[8:9], off nt
	v_lshl_add_u64 v[16:17], s[52:53], 0, v[18:19]
	s_add_i32 s24, s24, s42
	s_add_i32 s22, s22, s23
	s_cmpk_gt_i32 s24, 0x3ff
	s_waitcnt vmcnt(2)
	v_lshlrev_b32_e32 v26, 16, v12
	v_and_b32_e32 v27, 0xffff0000, v12
	v_lshlrev_b32_e32 v12, 16, v13
	v_and_b32_e32 v13, 0xffff0000, v13
	s_waitcnt vmcnt(1) lgkmcnt(1)
	v_pk_add_f32 v[4:5], v[4:5], v[22:23] op_sel_hi:[1,0]
	v_pk_add_f32 v[6:7], v[6:7], v[22:23] op_sel_hi:[1,0]
	v_pk_mul_f32 v[4:5], v[4:5], v[26:27]
	s_waitcnt vmcnt(0)
	v_lshlrev_b32_e32 v26, 16, v8
	v_and_b32_e32 v27, 0xffff0000, v8
	v_pk_mul_f32 v[6:7], v[6:7], v[12:13]
	v_lshlrev_b32_e32 v8, 16, v9
	v_and_b32_e32 v9, 0xffff0000, v9
	v_pk_mul_f32 v[6:7], v[6:7], v[8:9]
	s_waitcnt lgkmcnt(0)
	v_pk_add_f32 v[0:1], v[0:1], v[22:23] op_sel_hi:[1,0]
	v_lshlrev_b32_e32 v8, 16, v14
	v_and_b32_e32 v9, 0xffff0000, v14
	v_pk_mul_f32 v[0:1], v[0:1], v[8:9]
	v_lshlrev_b32_e32 v8, 16, v10
	v_and_b32_e32 v9, 0xffff0000, v10
	v_pk_mul_f32 v[8:9], v[0:1], v[8:9]
	v_pk_add_f32 v[0:1], v[2:3], v[22:23] op_sel_hi:[1,0]
	v_lshlrev_b32_e32 v2, 16, v15
	v_and_b32_e32 v3, 0xffff0000, v15
	v_pk_mul_f32 v[4:5], v[4:5], v[26:27]
	v_pk_mul_f32 v[0:1], v[0:1], v[2:3]
	v_lshlrev_b32_e32 v2, 16, v11
	v_and_b32_e32 v3, 0xffff0000, v11
	v_pk_mul_f32 v[10:11], v[0:1], v[2:3]
	v_cvt_pk_bf16_f32 v0, v4, v5
	v_lshlrev_b64 v[4:5], 12, v[20:21]
	v_cvt_pk_bf16_f32 v1, v6, v7
	v_cvt_pk_bf16_f32 v2, v8, v9
	v_cvt_pk_bf16_f32 v3, v10, v11
	v_lshl_add_u64 v[4:5], v[16:17], 0, v[4:5]
	global_store_dwordx4 v[4:5], v[0:3], off nt
	ds_read_b128 v[2:5], v24 offset:2112
	ds_read_b128 v[6:9], v24 offset:2128
	v_or_b32_e32 v0, s15, v23
	v_or_b32_e32 v14, s25, v0
	v_mad_i64_i32 v[0:1], s[2:3], v14, s69, v[66:67]
	v_lshl_add_u64 v[0:1], v[0:1], 0, v[18:19]
	global_load_dwordx4 v[10:13], v[0:1], off nt
	v_add_co_u32_e32 v0, vcc, s8, v0
	v_ashrrev_i32_e32 v15, 31, v14
	s_nop 0
	v_addc_co_u32_e32 v1, vcc, 0, v1, vcc
	global_load_dwordx4 v[26:29], v[0:1], off nt
	v_add_lshl_u32 v0, v23, s10, 2
	global_load_dword v20, v0, s[6:7] offset:16
	v_or_b32_e32 v1, s16, v23
	s_waitcnt vmcnt(2)
	v_lshlrev_b32_e32 v30, 16, v10
	v_and_b32_e32 v31, 0xffff0000, v10
	v_lshlrev_b32_e32 v10, 16, v11
	v_and_b32_e32 v11, 0xffff0000, v11
	s_waitcnt vmcnt(0) lgkmcnt(1)
	v_pk_add_f32 v[4:5], v[4:5], v[20:21] op_sel_hi:[1,0]
	s_nop 0
	v_pk_mul_f32 v[4:5], v[4:5], v[10:11]
	v_lshlrev_b32_e32 v10, 16, v27
	v_and_b32_e32 v11, 0xffff0000, v27
	v_pk_mul_f32 v[4:5], v[4:5], v[10:11]
	s_waitcnt lgkmcnt(0)
	v_pk_add_f32 v[6:7], v[6:7], v[20:21] op_sel_hi:[1,0]
	v_lshlrev_b32_e32 v10, 16, v12
	v_and_b32_e32 v11, 0xffff0000, v12
	v_pk_add_f32 v[2:3], v[2:3], v[20:21] op_sel_hi:[1,0]
	v_pk_mul_f32 v[6:7], v[6:7], v[10:11]
	v_lshlrev_b32_e32 v10, 16, v28
	v_and_b32_e32 v11, 0xffff0000, v28
	v_pk_mul_f32 v[2:3], v[2:3], v[30:31]
	v_lshlrev_b32_e32 v30, 16, v26
	v_and_b32_e32 v31, 0xffff0000, v26
	v_pk_mul_f32 v[6:7], v[6:7], v[10:11]
	v_pk_add_f32 v[8:9], v[8:9], v[20:21] op_sel_hi:[1,0]
	v_lshlrev_b32_e32 v10, 16, v13
	v_and_b32_e32 v11, 0xffff0000, v13
	v_pk_mul_f32 v[2:3], v[2:3], v[30:31]
	v_pk_mul_f32 v[8:9], v[8:9], v[10:11]
	v_lshlrev_b32_e32 v10, 16, v29
	v_and_b32_e32 v11, 0xffff0000, v29
	v_pk_mul_f32 v[8:9], v[8:9], v[10:11]
	v_cvt_pk_bf16_f32 v2, v2, v3
	v_cvt_pk_bf16_f32 v3, v4, v5
	v_cvt_pk_bf16_f32 v4, v6, v7
	v_lshlrev_b64 v[6:7], 12, v[14:15]
	v_or_b32_e32 v14, s25, v1
	v_cvt_pk_bf16_f32 v5, v8, v9
	v_lshl_add_u64 v[6:7], v[16:17], 0, v[6:7]
	v_mad_i64_i32 v[10:11], s[2:3], v14, s69, v[66:67]
	global_store_dwordx4 v[6:7], v[2:5], off nt
	v_lshl_add_u64 v[20:21], v[10:11], 0, v[18:19]
	ds_read_b128 v[2:5], v24 offset:4224
	ds_read_b128 v[6:9], v24 offset:4240
	global_load_dwordx4 v[10:13], v[20:21], off nt
	v_add_co_u32_e32 v20, vcc, s8, v20
	v_ashrrev_i32_e32 v15, 31, v14
	s_nop 0
	v_addc_co_u32_e32 v21, vcc, 0, v21, vcc
	global_load_dwordx4 v[26:29], v[20:21], off nt
	s_nop 0
	global_load_dword v20, v0, s[6:7] offset:32
	v_or_b32_e32 v1, s17, v23
	s_waitcnt vmcnt(2)
	v_lshlrev_b32_e32 v30, 16, v10
	v_and_b32_e32 v31, 0xffff0000, v10
	v_lshlrev_b32_e32 v10, 16, v11
	v_and_b32_e32 v11, 0xffff0000, v11
	s_waitcnt vmcnt(0) lgkmcnt(1)
	v_pk_add_f32 v[4:5], v[4:5], v[20:21] op_sel_hi:[1,0]
	s_nop 0
	v_pk_mul_f32 v[4:5], v[4:5], v[10:11]
	v_lshlrev_b32_e32 v10, 16, v27
	v_and_b32_e32 v11, 0xffff0000, v27
	v_pk_mul_f32 v[4:5], v[4:5], v[10:11]
	s_waitcnt lgkmcnt(0)
	v_pk_add_f32 v[6:7], v[6:7], v[20:21] op_sel_hi:[1,0]
	v_lshlrev_b32_e32 v10, 16, v12
	v_and_b32_e32 v11, 0xffff0000, v12
	v_pk_add_f32 v[2:3], v[2:3], v[20:21] op_sel_hi:[1,0]
	v_pk_mul_f32 v[6:7], v[6:7], v[10:11]
	v_lshlrev_b32_e32 v10, 16, v28
	v_and_b32_e32 v11, 0xffff0000, v28
	v_pk_mul_f32 v[2:3], v[2:3], v[30:31]
	v_lshlrev_b32_e32 v30, 16, v26
	v_and_b32_e32 v31, 0xffff0000, v26
	v_pk_mul_f32 v[6:7], v[6:7], v[10:11]
	v_pk_add_f32 v[8:9], v[8:9], v[20:21] op_sel_hi:[1,0]
	v_lshlrev_b32_e32 v10, 16, v13
	v_and_b32_e32 v11, 0xffff0000, v13
	v_pk_mul_f32 v[2:3], v[2:3], v[30:31]
	v_pk_mul_f32 v[8:9], v[8:9], v[10:11]
	v_lshlrev_b32_e32 v10, 16, v29
	v_and_b32_e32 v11, 0xffff0000, v29
	v_pk_mul_f32 v[8:9], v[8:9], v[10:11]
	v_cvt_pk_bf16_f32 v2, v2, v3
	v_cvt_pk_bf16_f32 v3, v4, v5
	v_cvt_pk_bf16_f32 v4, v6, v7
	v_lshlrev_b64 v[6:7], 12, v[14:15]
	v_or_b32_e32 v14, s25, v1
	v_cvt_pk_bf16_f32 v5, v8, v9
	v_lshl_add_u64 v[6:7], v[16:17], 0, v[6:7]
	v_mad_i64_i32 v[10:11], s[2:3], v14, s69, v[66:67]
	global_store_dwordx4 v[6:7], v[2:5], off nt
	v_lshl_add_u64 v[20:21], v[10:11], 0, v[18:19]
	ds_read_b128 v[2:5], v24 offset:6336
	ds_read_b128 v[6:9], v24 offset:6352
	global_load_dwordx4 v[10:13], v[20:21], off nt
	v_add_co_u32_e32 v20, vcc, s8, v20
	v_ashrrev_i32_e32 v15, 31, v14
	s_nop 0
	v_addc_co_u32_e32 v21, vcc, 0, v21, vcc
	global_load_dwordx4 v[26:29], v[20:21], off nt
	s_nop 0
	global_load_dword v20, v0, s[6:7] offset:48
	v_or_b32_e32 v1, s18, v23
	s_waitcnt vmcnt(2)
	v_lshlrev_b32_e32 v30, 16, v10
	v_and_b32_e32 v31, 0xffff0000, v10
	v_lshlrev_b32_e32 v10, 16, v11
	v_and_b32_e32 v11, 0xffff0000, v11
	s_waitcnt vmcnt(0) lgkmcnt(1)
	v_pk_add_f32 v[4:5], v[4:5], v[20:21] op_sel_hi:[1,0]
	s_nop 0
	v_pk_mul_f32 v[4:5], v[4:5], v[10:11]
	v_lshlrev_b32_e32 v10, 16, v27
	v_and_b32_e32 v11, 0xffff0000, v27
	v_pk_mul_f32 v[4:5], v[4:5], v[10:11]
	s_waitcnt lgkmcnt(0)
	v_pk_add_f32 v[6:7], v[6:7], v[20:21] op_sel_hi:[1,0]
	v_lshlrev_b32_e32 v10, 16, v12
	v_and_b32_e32 v11, 0xffff0000, v12
	v_pk_add_f32 v[2:3], v[2:3], v[20:21] op_sel_hi:[1,0]
	v_pk_mul_f32 v[6:7], v[6:7], v[10:11]
	v_lshlrev_b32_e32 v10, 16, v28
	v_and_b32_e32 v11, 0xffff0000, v28
	v_pk_mul_f32 v[2:3], v[2:3], v[30:31]
	v_lshlrev_b32_e32 v30, 16, v26
	v_and_b32_e32 v31, 0xffff0000, v26
	v_pk_mul_f32 v[6:7], v[6:7], v[10:11]
	v_pk_add_f32 v[8:9], v[8:9], v[20:21] op_sel_hi:[1,0]
	v_lshlrev_b32_e32 v10, 16, v13
	v_and_b32_e32 v11, 0xffff0000, v13
	v_pk_mul_f32 v[2:3], v[2:3], v[30:31]
	v_pk_mul_f32 v[8:9], v[8:9], v[10:11]
	v_lshlrev_b32_e32 v10, 16, v29
	v_and_b32_e32 v11, 0xffff0000, v29
	v_pk_mul_f32 v[8:9], v[8:9], v[10:11]
	v_cvt_pk_bf16_f32 v2, v2, v3
	v_cvt_pk_bf16_f32 v3, v4, v5
	v_cvt_pk_bf16_f32 v4, v6, v7
	v_lshlrev_b64 v[6:7], 12, v[14:15]
	v_or_b32_e32 v14, s25, v1
	v_cvt_pk_bf16_f32 v5, v8, v9
	v_lshl_add_u64 v[6:7], v[16:17], 0, v[6:7]
	v_mad_i64_i32 v[10:11], s[2:3], v14, s69, v[66:67]
	global_store_dwordx4 v[6:7], v[2:5], off nt
	v_lshl_add_u64 v[20:21], v[10:11], 0, v[18:19]
	ds_read_b128 v[2:5], v24 offset:8448
	ds_read_b128 v[6:9], v24 offset:8464
	global_load_dwordx4 v[10:13], v[20:21], off nt
	v_add_co_u32_e32 v20, vcc, s8, v20
	v_ashrrev_i32_e32 v15, 31, v14
	s_nop 0
	v_addc_co_u32_e32 v21, vcc, 0, v21, vcc
	global_load_dwordx4 v[26:29], v[20:21], off nt
	s_nop 0
	global_load_dword v20, v0, s[6:7] offset:64
	v_or_b32_e32 v1, s19, v23
	s_waitcnt vmcnt(2)
	v_lshlrev_b32_e32 v30, 16, v10
	v_and_b32_e32 v31, 0xffff0000, v10
	v_lshlrev_b32_e32 v10, 16, v11
	v_and_b32_e32 v11, 0xffff0000, v11
	s_waitcnt vmcnt(0) lgkmcnt(1)
	v_pk_add_f32 v[4:5], v[4:5], v[20:21] op_sel_hi:[1,0]
	s_nop 0
	v_pk_mul_f32 v[4:5], v[4:5], v[10:11]
	v_lshlrev_b32_e32 v10, 16, v27
	v_and_b32_e32 v11, 0xffff0000, v27
	v_pk_mul_f32 v[4:5], v[4:5], v[10:11]
	s_waitcnt lgkmcnt(0)
	v_pk_add_f32 v[6:7], v[6:7], v[20:21] op_sel_hi:[1,0]
	v_lshlrev_b32_e32 v10, 16, v12
	v_and_b32_e32 v11, 0xffff0000, v12
	v_pk_add_f32 v[2:3], v[2:3], v[20:21] op_sel_hi:[1,0]
	v_pk_mul_f32 v[6:7], v[6:7], v[10:11]
	v_lshlrev_b32_e32 v10, 16, v28
	v_and_b32_e32 v11, 0xffff0000, v28
	v_pk_mul_f32 v[2:3], v[2:3], v[30:31]
	v_lshlrev_b32_e32 v30, 16, v26
	v_and_b32_e32 v31, 0xffff0000, v26
	v_pk_mul_f32 v[6:7], v[6:7], v[10:11]
	v_pk_add_f32 v[8:9], v[8:9], v[20:21] op_sel_hi:[1,0]
	v_lshlrev_b32_e32 v10, 16, v13
	v_and_b32_e32 v11, 0xffff0000, v13
	v_pk_mul_f32 v[2:3], v[2:3], v[30:31]
	v_pk_mul_f32 v[8:9], v[8:9], v[10:11]
	v_lshlrev_b32_e32 v10, 16, v29
	v_and_b32_e32 v11, 0xffff0000, v29
	v_pk_mul_f32 v[8:9], v[8:9], v[10:11]
	v_cvt_pk_bf16_f32 v2, v2, v3
	v_cvt_pk_bf16_f32 v3, v4, v5
	v_cvt_pk_bf16_f32 v4, v6, v7
	v_lshlrev_b64 v[6:7], 12, v[14:15]
	v_or_b32_e32 v14, s25, v1
	v_cvt_pk_bf16_f32 v5, v8, v9
	v_lshl_add_u64 v[6:7], v[16:17], 0, v[6:7]
	v_mad_i64_i32 v[10:11], s[2:3], v14, s69, v[66:67]
	global_store_dwordx4 v[6:7], v[2:5], off nt
	v_lshl_add_u64 v[20:21], v[10:11], 0, v[18:19]
	ds_read_b128 v[2:5], v24 offset:10560
	ds_read_b128 v[6:9], v24 offset:10576
	global_load_dwordx4 v[10:13], v[20:21], off nt
	v_add_co_u32_e32 v20, vcc, s8, v20
	v_ashrrev_i32_e32 v15, 31, v14
	s_nop 0
	v_addc_co_u32_e32 v21, vcc, 0, v21, vcc
	global_load_dwordx4 v[26:29], v[20:21], off nt
	s_nop 0
	global_load_dword v20, v0, s[6:7] offset:80
	v_or_b32_e32 v1, s20, v23
	s_waitcnt vmcnt(2)
	v_lshlrev_b32_e32 v30, 16, v10
	v_and_b32_e32 v31, 0xffff0000, v10
	v_lshlrev_b32_e32 v10, 16, v11
	v_and_b32_e32 v11, 0xffff0000, v11
	s_waitcnt vmcnt(0) lgkmcnt(1)
	v_pk_add_f32 v[4:5], v[4:5], v[20:21] op_sel_hi:[1,0]
	s_nop 0
	v_pk_mul_f32 v[4:5], v[4:5], v[10:11]
	v_lshlrev_b32_e32 v10, 16, v27
	v_and_b32_e32 v11, 0xffff0000, v27
	v_pk_mul_f32 v[4:5], v[4:5], v[10:11]
	s_waitcnt lgkmcnt(0)
	v_pk_add_f32 v[6:7], v[6:7], v[20:21] op_sel_hi:[1,0]
	v_lshlrev_b32_e32 v10, 16, v12
	v_and_b32_e32 v11, 0xffff0000, v12
	v_pk_add_f32 v[2:3], v[2:3], v[20:21] op_sel_hi:[1,0]
	v_pk_mul_f32 v[6:7], v[6:7], v[10:11]
	v_lshlrev_b32_e32 v10, 16, v28
	v_and_b32_e32 v11, 0xffff0000, v28
	v_pk_mul_f32 v[2:3], v[2:3], v[30:31]
	v_lshlrev_b32_e32 v30, 16, v26
	v_and_b32_e32 v31, 0xffff0000, v26
	v_pk_mul_f32 v[6:7], v[6:7], v[10:11]
	v_pk_add_f32 v[8:9], v[8:9], v[20:21] op_sel_hi:[1,0]
	v_lshlrev_b32_e32 v10, 16, v13
	v_and_b32_e32 v11, 0xffff0000, v13
	v_pk_mul_f32 v[2:3], v[2:3], v[30:31]
	v_pk_mul_f32 v[8:9], v[8:9], v[10:11]
	v_lshlrev_b32_e32 v10, 16, v29
	v_and_b32_e32 v11, 0xffff0000, v29
	v_pk_mul_f32 v[8:9], v[8:9], v[10:11]
	v_cvt_pk_bf16_f32 v2, v2, v3
	v_cvt_pk_bf16_f32 v3, v4, v5
	v_cvt_pk_bf16_f32 v4, v6, v7
	v_lshlrev_b64 v[6:7], 12, v[14:15]
	v_or_b32_e32 v14, s25, v1
	v_cvt_pk_bf16_f32 v5, v8, v9
	v_lshl_add_u64 v[6:7], v[16:17], 0, v[6:7]
	v_mad_i64_i32 v[10:11], s[2:3], v14, s69, v[66:67]
	global_store_dwordx4 v[6:7], v[2:5], off nt
	v_lshl_add_u64 v[20:21], v[10:11], 0, v[18:19]
	ds_read_b128 v[2:5], v24 offset:12672
	ds_read_b128 v[6:9], v24 offset:12688
	global_load_dwordx4 v[10:13], v[20:21], off nt
	v_add_co_u32_e32 v20, vcc, s8, v20
	v_ashrrev_i32_e32 v15, 31, v14
	s_nop 0
	v_addc_co_u32_e32 v21, vcc, 0, v21, vcc
	global_load_dwordx4 v[26:29], v[20:21], off nt
	s_nop 0
	global_load_dword v20, v0, s[6:7] offset:96
	v_or_b32_e32 v1, s21, v23
	s_waitcnt vmcnt(2)
	v_lshlrev_b32_e32 v30, 16, v10
	v_and_b32_e32 v31, 0xffff0000, v10
	v_lshlrev_b32_e32 v10, 16, v11
	v_and_b32_e32 v11, 0xffff0000, v11
	s_waitcnt vmcnt(0) lgkmcnt(1)
	v_pk_add_f32 v[4:5], v[4:5], v[20:21] op_sel_hi:[1,0]
	s_nop 0
	v_pk_mul_f32 v[4:5], v[4:5], v[10:11]
	v_lshlrev_b32_e32 v10, 16, v27
	v_and_b32_e32 v11, 0xffff0000, v27
	v_pk_mul_f32 v[4:5], v[4:5], v[10:11]
	s_waitcnt lgkmcnt(0)
	v_pk_add_f32 v[6:7], v[6:7], v[20:21] op_sel_hi:[1,0]
	v_lshlrev_b32_e32 v10, 16, v12
	v_and_b32_e32 v11, 0xffff0000, v12
	v_pk_add_f32 v[2:3], v[2:3], v[20:21] op_sel_hi:[1,0]
	v_pk_mul_f32 v[6:7], v[6:7], v[10:11]
	v_lshlrev_b32_e32 v10, 16, v28
	v_and_b32_e32 v11, 0xffff0000, v28
	v_pk_mul_f32 v[2:3], v[2:3], v[30:31]
	v_lshlrev_b32_e32 v30, 16, v26
	v_and_b32_e32 v31, 0xffff0000, v26
	v_pk_mul_f32 v[6:7], v[6:7], v[10:11]
	v_pk_add_f32 v[8:9], v[8:9], v[20:21] op_sel_hi:[1,0]
	v_lshlrev_b32_e32 v10, 16, v13
	v_and_b32_e32 v11, 0xffff0000, v13
	v_pk_mul_f32 v[2:3], v[2:3], v[30:31]
	v_pk_mul_f32 v[8:9], v[8:9], v[10:11]
	v_lshlrev_b32_e32 v10, 16, v29
	v_and_b32_e32 v11, 0xffff0000, v29
	v_pk_mul_f32 v[8:9], v[8:9], v[10:11]
	v_cvt_pk_bf16_f32 v2, v2, v3
	v_cvt_pk_bf16_f32 v3, v4, v5
	v_cvt_pk_bf16_f32 v4, v6, v7
	v_lshlrev_b64 v[6:7], 12, v[14:15]
	v_or_b32_e32 v14, s25, v1
	v_cvt_pk_bf16_f32 v5, v8, v9
	v_lshl_add_u64 v[6:7], v[16:17], 0, v[6:7]
	v_mad_i64_i32 v[10:11], s[2:3], v14, s69, v[66:67]
	global_store_dwordx4 v[6:7], v[2:5], off nt
	v_lshl_add_u64 v[18:19], v[10:11], 0, v[18:19]
	ds_read_b128 v[2:5], v24 offset:14784
	ds_read_b128 v[6:9], v24 offset:14800
	global_load_dwordx4 v[10:13], v[18:19], off nt
	v_add_co_u32_e32 v18, vcc, s8, v18
	v_ashrrev_i32_e32 v15, 31, v14
	s_nop 0
	v_addc_co_u32_e32 v19, vcc, 0, v19, vcc
	global_load_dwordx4 v[18:21], v[18:19], off nt
	s_nop 0
	global_load_dword v0, v0, s[6:7] offset:112
	s_waitcnt vmcnt(2)
	v_lshlrev_b32_e32 v22, 16, v10
	v_and_b32_e32 v23, 0xffff0000, v10
	v_lshlrev_b32_e32 v10, 16, v11
	v_and_b32_e32 v11, 0xffff0000, v11
	s_waitcnt vmcnt(0) lgkmcnt(1)
	v_pk_add_f32 v[4:5], v[4:5], v[0:1] op_sel_hi:[1,0]
	s_nop 0
	v_pk_mul_f32 v[4:5], v[4:5], v[10:11]
	v_lshlrev_b32_e32 v10, 16, v19
	v_and_b32_e32 v11, 0xffff0000, v19
	v_pk_add_f32 v[2:3], v[2:3], v[0:1] op_sel_hi:[1,0]
	v_pk_mul_f32 v[4:5], v[4:5], v[10:11]
	s_waitcnt lgkmcnt(0)
	v_pk_add_f32 v[6:7], v[6:7], v[0:1] op_sel_hi:[1,0]
	v_lshlrev_b32_e32 v10, 16, v12
	v_and_b32_e32 v11, 0xffff0000, v12
	v_pk_add_f32 v[0:1], v[8:9], v[0:1] op_sel_hi:[1,0]
	v_lshlrev_b32_e32 v8, 16, v13
	v_and_b32_e32 v9, 0xffff0000, v13
	v_pk_mul_f32 v[2:3], v[2:3], v[22:23]
	v_lshlrev_b32_e32 v22, 16, v18
	v_and_b32_e32 v23, 0xffff0000, v18
	v_pk_mul_f32 v[6:7], v[6:7], v[10:11]
	v_lshlrev_b32_e32 v10, 16, v20
	v_and_b32_e32 v11, 0xffff0000, v20
	v_pk_mul_f32 v[0:1], v[0:1], v[8:9]
	v_lshlrev_b32_e32 v8, 16, v21
	v_and_b32_e32 v9, 0xffff0000, v21
	v_pk_mul_f32 v[2:3], v[2:3], v[22:23]
	v_pk_mul_f32 v[6:7], v[6:7], v[10:11]
	v_pk_mul_f32 v[8:9], v[0:1], v[8:9]
	v_cvt_pk_bf16_f32 v1, v4, v5
	v_lshlrev_b64 v[4:5], 12, v[14:15]
	v_cvt_pk_bf16_f32 v0, v2, v3
	v_cvt_pk_bf16_f32 v2, v6, v7
	v_cvt_pk_bf16_f32 v3, v8, v9
	v_lshl_add_u64 v[4:5], v[16:17], 0, v[4:5]
	global_store_dwordx4 v[4:5], v[0:3], off nt
	s_cbranch_scc1 .LBB0_269
